# attention: next key tile's four K loads issued right behind the current tile's QK^T MFMAs (software prefetch into v212-227, fills the MFMA result wait); skipped tiles never fetched
# speedup vs baseline: 1.0084x; 1.0084x over previous
.LBB0_625:
	s_ashr_i32 s18, s38, 12
	s_bfe_u32 s4, s38, 0x20007
	s_and_b32 s39, s38, 0x7f
	s_cmp_eq_u32 s18, 1
	s_cselect_b32 s2, 4, 16
	s_cselect_b32 s3, 2, 4
	s_cmpk_lt_u32 s38, 0x1000
	s_cselect_b32 s46, 1, s2
	s_cselect_b32 s19, 0, s3
	s_lshl_b32 s2, s18, 2
	s_or_b32 s47, s2, s4
	s_add_i32 s2, s47, 1
	v_cvt_f32_i32_e32 v0, s2
	s_xor_b32 s2, s19, 7
	s_lshr_b32 s49, s39, s2
	s_lshr_b32 s48, 0x80, s19
	v_mul_f32_e32 v0, 0xc1000000, v0
	v_div_scale_f32 v2, s[2:3], s15, s15, v0
	v_rcp_f32_e32 v3, v2
	s_add_i32 s48, s48, -1
	s_and_b32 s2, s48, s39
	s_lshl_b32 s39, s2, 5
	v_fma_f32 v4, -v2, v3, 1.0
	v_fmac_f32_e32 v3, v4, v3
	v_div_scale_f32 v4, vcc, v0, s15, v0
	v_mul_f32_e32 v5, v4, v3
	v_fma_f32 v6, -v2, v5, v4
	v_fmac_f32_e32 v5, v6, v3
	v_fma_f32 v2, -v2, v5, v4
	v_div_fmas_f32 v2, v2, v3, v5
	v_div_fixup_f32 v0, v2, s15, v0
	v_cmp_gt_f32_e32 vcc, s17, v0
	s_and_b64 s[2:3], vcc, exec
	s_cselect_b32 s48, 0xffffffc0, 0
	s_lshl_b32 s2, s38, 3
	s_and_b32 s2, s2, 0x7000
	v_or_b32_e32 v2, s39, v118
	s_or_b32 s49, s49, s2
	v_lshlrev_b32_e32 v2, s19, v2
	v_add_u32_e32 v92, s49, v2
	v_mad_u64_u32 v[2:3], s[2:3], v92, s20, v[82:83]
	s_lshl_b32 s2, s47, 6
	s_ashr_i32 s3, s2, 31
	s_lshl_b64 s[2:3], s[2:3], 1
	v_lshl_add_u64 v[94:95], v[2:3], 0, s[2:3]
	v_lshl_add_u64 v[2:3], v[94:95], 0, v[84:85]
	global_load_dwordx4 v[50:53], v[2:3], off
	global_load_dwordx4 v[54:57], v[2:3], off offset:32
	global_load_dwordx4 v[58:61], v[2:3], off offset:64
	global_load_dwordx4 v[62:65], v[2:3], off offset:96
	v_cndmask_b32_e32 v4, 0, v122, vcc
	v_add_f32_e32 v0, v0, v4
	v_exp_f32_e32 v0, v0
	s_mulk_i32 s49, 0x1200
	v_cvt_f32_ubyte0_e32 v2, s46
	s_add_u32 s46, s30, s49
	v_ldexp_f32 v0, v0, s48
	v_mul_f32_e32 v0, v0, v2
	s_addc_u32 s47, s31, 0
	v_mov_b32_e32 v14, v1
	v_mov_b32_e32 v15, v1
	v_mul_f32_e32 v97, 0x3fb8aa3b, v0
	s_add_u32 s2, s46, s2
	v_mov_b32_e32 v0, v1
	v_mov_b32_e32 v2, v1
	v_mov_b32_e32 v3, v1
	v_mov_b32_e32 v4, v1
	v_mov_b32_e32 v5, v1
	v_mov_b32_e32 v6, v1
	v_mov_b32_e32 v7, v1
	v_mov_b32_e32 v8, v1
	v_mov_b32_e32 v9, v1
	v_mov_b32_e32 v10, v1
	v_mov_b32_e32 v11, v1
	v_mov_b32_e32 v12, v1
	v_mov_b32_e32 v13, v1
	v_mov_b64_e32 v[32:33], v[14:15]
	s_addc_u32 s3, s47, s3
	v_mov_b64_e32 v[30:31], v[12:13]
	v_mov_b64_e32 v[28:29], v[10:11]
	v_mov_b64_e32 v[26:27], v[8:9]
	v_mov_b64_e32 v[24:25], v[6:7]
	v_mov_b64_e32 v[22:23], v[4:5]
	v_mov_b64_e32 v[20:21], v[2:3]
	v_mov_b64_e32 v[18:19], v[0:1]
	v_mov_b64_e32 v[16:17], v[14:15]
	v_mov_b32_e32 v93, v1
	v_lshl_add_u64 v[98:99], s[2:3], 0, v[86:87]
	v_lshl_add_u64 v[100:101], s[2:3], 0, v[84:85]
	v_mov_b32_e32 v102, v97
	v_mov_b32_e32 v103, v97
	v_or_b32_e32 v89, s39, v119
	v_add_u32_e32 v131, s39, v121
	v_mov_b32_e32 v133, 0xf149f2ca
	v_mov_b32_e32 v130, v1
	v_mov_b64_e32 v[14:15], v[12:13]
	v_mov_b64_e32 v[12:13], v[10:11]
	v_mov_b64_e32 v[10:11], v[8:9]
	v_mov_b64_e32 v[8:9], v[6:7]
	v_mov_b64_e32 v[6:7], v[4:5]
	v_mov_b64_e32 v[4:5], v[2:3]
	v_mov_b64_e32 v[2:3], v[0:1]
	s_lshr_b32 s54, s39, 5
	s_mul_i32 s55, s54, 0xcd
	s_lshr_b32 s55, s55, 10
	s_mul_i32 s55, s55, 5
	s_sub_i32 s54, s54, s55
	s_sub_i32 s54, 4, s54
	s_lshl_b32 s46, s54, 5
	v_subrev_u32_e32 v132, s46, v120
	s_mov_b32 s56, 5
	s_mov_b32 s98, s46
	s_add_i32 s99, s39, s98
	s_addk_i32 s99, 0xff80
	s_cmp_lt_i32 s99, 0
	s_cbranch_scc1 .Lmy_kpf_p
	v_add_u32_e32 v228, s98, v131
	v_mov_b32_e32 v229, 0
	v_lshlrev_b64 v[230:231], s19, v[228:229]
	v_mad_u64_u32 v[232:233], s[100:101], v230, s20, v[100:101]
	v_mad_u32_u24 v233, v231, s20, v233
	global_load_dwordx4 v[212:215], v[232:233], off offset:1536
	global_load_dwordx4 v[216:219], v[232:233], off offset:1568
	global_load_dwordx4 v[220:223], v[232:233], off offset:1600
	global_load_dwordx4 v[224:227], v[232:233], off offset:1632

.Lmy_kpf_skip:
	s_cmp_eq_u32 s56, 1
	s_cbranch_scc1 .Lmy_kpf_s
	s_add_i32 s98, s46, 32
	s_cmpk_lg_i32 s98, 0xa0
	s_cselect_b32 s98, s98, 0
	s_add_i32 s99, s39, s98
	s_addk_i32 s99, 0xff80
	s_cmp_lt_i32 s99, 0
	s_cbranch_scc1 .Lmy_kpf_s
	v_add_u32_e32 v228, s98, v131
	v_mov_b32_e32 v229, 0
	v_lshlrev_b64 v[230:231], s19, v[228:229]
	v_mad_u64_u32 v[232:233], s[100:101], v230, s20, v[100:101]
	v_mad_u32_u24 v233, v231, s20, v233
	global_load_dwordx4 v[212:215], v[232:233], off offset:1536
	global_load_dwordx4 v[216:219], v[232:233], off offset:1568
	global_load_dwordx4 v[220:223], v[232:233], off offset:1600
	global_load_dwordx4 v[224:227], v[232:233], off offset:1632
.Lmy_kpf_s:
.LBB0_626:
	s_add_i32 s46, s46, 32
	v_subrev_u32_e32 v132, 32, v132
	s_cmpk_lg_i32 s46, 0xa0
	s_cbranch_scc1 .Lmy_attn_nowrap
	s_mov_b32 s46, 0
	v_add_u32_e32 v132, 0xa0, v132

.LBB0_627:
	s_add_i32 s2, s39, s46
	s_addk_i32 s2, 0xff80
	s_cmp_lt_i32 s2, 0
	s_cbranch_scc1 .Lmy_kpf_skip
	v_add_u32_e32 v34, s46, v89
	v_add_u32_e32 v0, 0xffffff80, v34
	v_lshlrev_b64 v[38:39], s19, v[0:1]
	v_add_u32_e32 v0, 0xffffff88, v34
	v_lshlrev_b64 v[114:115], s19, v[0:1]
	v_add_u32_e32 v0, 0xffffff90, v34
	v_lshlrev_b64 v[150:151], s19, v[0:1]
	v_add_u32_e32 v0, 0xffffff98, v34
	v_lshlrev_b64 v[152:153], s19, v[0:1]
	v_mad_u64_u32 v[40:41], s[2:3], v38, s20, v[98:99]
	v_mad_u32_u24 v41, v39, s20, v41
	v_and_b32_e32 v38, 64, v125
	global_load_dwordx4 v[146:149], v[40:41], off offset:3072
	v_add_u32_e32 v96, 64, v38
	v_add_u32_e32 v175, v132, v67
	v_add_u32_e32 v176, v132, v66
	v_cvt_f32_i32_e32 v157, v175
	v_cvt_f32_i32_e32 v156, v176
	v_add_u32_e32 v177, v69, v132
	v_add_u32_e32 v178, v68, v132
	v_cvt_f32_i32_e32 v159, v177
	v_cvt_f32_i32_e32 v158, v178
	v_xor_b32_e32 v0, 32, v125
	v_add_u32_e32 v168, v74, v132
	v_add_u32_e32 v179, v71, v132
	v_add_u32_e32 v180, v70, v132
	v_cvt_f32_i32_e32 v91, v168
	v_cvt_f32_i32_e32 v161, v179
	v_cvt_f32_i32_e32 v160, v180
	v_cmp_lt_i32_e32 vcc, v0, v96
	v_pk_mul_f32 v[156:157], v[102:103], v[156:157]
	v_pk_mul_f32 v[158:159], v[102:103], v[158:159]
	v_cndmask_b32_e32 v0, v125, v0, vcc
	v_cmp_gt_u32_e32 vcc, s21, v175
	v_lshlrev_b32_e32 v184, 2, v0
	v_add_u32_e32 v163, v75, v132
	v_mad_u64_u32 v[166:167], s[2:3], v114, s20, v[98:99]
	v_pk_mul_f32 v[160:161], v[102:103], v[160:161]
	v_mad_u32_u24 v167, v115, s20, v167
	v_mad_u64_u32 v[114:115], s[2:3], v150, s20, v[98:99]
	v_mad_u32_u24 v115, v151, s20, v115
	v_mad_u64_u32 v[150:151], s[2:3], v152, s20, v[98:99]
	v_mov_b32_e32 v155, v97
	v_add_u32_e32 v170, v76, v132
	v_mad_u32_u24 v151, v153, s20, v151
	global_load_dwordx4 v[186:189], v[166:167], off offset:3072
	global_load_dwordx4 v[190:193], v[114:115], off offset:3072
	global_load_dwordx4 v[194:197], v[150:151], off offset:3072
	v_mov_b32_e32 v117, v97
	v_add_u32_e32 v169, v77, v132
	v_mov_b32_e32 v113, v97
	v_add_u32_e32 v172, v78, v132
	v_mov_b32_e32 v111, v97
	v_add_u32_e32 v174, v80, v132
	v_mov_b32_e32 v109, v97
	v_add_u32_e32 v171, v79, v132
	v_mov_b32_e32 v107, v97
	v_add_u32_e32 v173, v81, v132
	v_mov_b32_e32 v105, v97
	v_add_u32_e32 v182, v73, v132
	v_add_u32_e32 v183, v72, v132
	v_cvt_f32_i32_e32 v165, v182
	v_cvt_f32_i32_e32 v164, v183
	s_waitcnt vmcnt(7)
	v_mfma_f32_32x32x16_bf16 v[34:49], v[212:215], v[50:53], 0
	s_waitcnt vmcnt(6)
	v_mfma_f32_32x32x16_bf16 v[34:49], v[216:219], v[54:57], v[34:49]
	s_waitcnt vmcnt(5)
	v_mfma_f32_32x32x16_bf16 v[34:49], v[220:223], v[58:61], v[34:49]
	s_waitcnt vmcnt(3)
	ds_write_b128 v123, v[146:149]
	s_waitcnt vmcnt(2)
	ds_write_b128 v123, v[186:189] offset:1024
	s_waitcnt vmcnt(1)
	ds_write_b128 v123, v[190:193] offset:2048
	s_waitcnt vmcnt(0)
	ds_write_b128 v123, v[194:197] offset:3072
	v_mfma_f32_32x32x16_bf16 v[34:49], v[224:227], v[62:65], v[34:49]
	s_waitcnt lgkmcnt(0)
	s_cmp_eq_u32 s56, 1
	s_cbranch_scc1 .Lmy_kpf_b
	s_add_i32 s98, s46, 32
	s_cmpk_lg_i32 s98, 0xa0
	s_cselect_b32 s98, s98, 0
	s_add_i32 s99, s39, s98
	s_addk_i32 s99, 0xff80
	s_cmp_lt_i32 s99, 0
	s_cbranch_scc1 .Lmy_kpf_b
	v_add_u32_e32 v228, s98, v131
	v_mov_b32_e32 v229, 0
	v_lshlrev_b64 v[230:231], s19, v[228:229]
	v_mad_u64_u32 v[232:233], s[100:101], v230, s20, v[100:101]
	v_mad_u32_u24 v233, v231, s20, v233
	global_load_dwordx4 v[212:215], v[232:233], off offset:1536
	global_load_dwordx4 v[216:219], v[232:233], off offset:1568
	global_load_dwordx4 v[220:223], v[232:233], off offset:1600
	global_load_dwordx4 v[224:227], v[232:233], off offset:1632
.Lmy_kpf_b:
	s_nop 11
	v_mov_b32_e32 v96, v42
	v_mov_b32_e32 v116, v43
	v_mov_b32_e32 v42, v34
	v_mov_b32_e32 v43, v36
	v_pk_fma_f32 v[42:43], v[42:43], s[16:17], v[156:157] op_sel_hi:[1,0,1] neg_lo:[0,0,1] neg_hi:[0,0,1]
	v_mov_b32_e32 v36, v35
	v_cndmask_b32_e32 v0, v126, v43, vcc
	v_cmp_gt_u32_e32 vcc, s21, v176
	v_mov_b32_e32 v110, v46
	v_pk_fma_f32 v[36:37], v[36:37], s[16:17], v[158:159] op_sel_hi:[1,0,1] neg_lo:[0,0,1] neg_hi:[0,0,1]
	v_cndmask_b32_e32 v46, v126, v42, vcc
	v_cmp_gt_u32_e32 vcc, s21, v177
	v_mov_b32_e32 v108, v47
	v_mov_b32_e32 v34, v38
	v_mov_b32_e32 v35, v40
	v_mov_b32_e32 v40, v39
	v_pk_mul_f32 v[38:39], v[96:97], v[90:91]
	v_cvt_f32_i32_e32 v91, v163
	v_cndmask_b32_e32 v47, v126, v37, vcc
	v_cmp_gt_u32_e32 vcc, s21, v178
	v_mov_b32_e32 v106, v48
	v_pk_fma_f32 v[34:35], v[34:35], s[16:17], v[160:161] op_sel_hi:[1,0,1] neg_lo:[0,0,1] neg_hi:[0,0,1]
	v_cndmask_b32_e32 v48, v126, v36, vcc
	v_cmp_gt_u32_e32 vcc, s21, v179
	v_mov_b32_e32 v104, v49
	v_mov_b32_e32 v154, v44
	v_cndmask_b32_e32 v49, v126, v35, vcc
	v_cmp_gt_u32_e32 vcc, s21, v180
	v_mov_b32_e32 v112, v45
	v_mov_b32_e32 v44, v38
	v_cndmask_b32_e32 v96, v126, v34, vcc
	v_max3_f32 v34, v46, s22, v48
	v_max3_f32 v114, v34, v0, v47
	v_pk_mul_f32 v[34:35], v[154:155], v[90:91]
	v_cvt_f32_i32_e32 v91, v170
	v_mov_b32_e32 v45, v34
	v_mov_b32_e32 v34, v39
	v_pk_add_f32 v[34:35], v[44:45], v[34:35] neg_lo:[0,1] neg_hi:[0,1]
	v_pk_mul_f32 v[36:37], v[116:117], v[90:91]
	v_cvt_f32_i32_e32 v91, v169
	v_cmp_gt_u32_e32 vcc, s21, v163
	v_mov_b32_e32 v38, v36
	s_nop 0
	v_cndmask_b32_e32 v44, v126, v35, vcc
	v_cmp_gt_u32_e32 vcc, s21, v168
	s_nop 1
	v_cndmask_b32_e32 v45, v126, v34, vcc
	v_pk_mul_f32 v[34:35], v[112:113], v[90:91]
	v_cvt_f32_i32_e32 v91, v172
	v_mov_b32_e32 v39, v34
	v_mov_b32_e32 v34, v37
	v_pk_add_f32 v[34:35], v[38:39], v[34:35] neg_lo:[0,1] neg_hi:[0,1]
	v_pk_mul_f32 v[36:37], v[110:111], v[90:91]
	v_cvt_f32_i32_e32 v91, v174
	v_cmp_gt_u32_e32 vcc, s21, v169
	v_pk_mul_f32 v[38:39], v[108:109], v[90:91]
	v_cvt_f32_i32_e32 v91, v171
	v_cndmask_b32_e32 v110, v126, v35, vcc
	v_cmp_gt_u32_e32 vcc, s21, v170
	v_pk_mul_f32 v[42:43], v[106:107], v[90:91]
	v_cvt_f32_i32_e32 v91, v173
	v_cndmask_b32_e32 v108, v126, v34, vcc
	v_mov_b32_e32 v34, v36
	v_mov_b32_e32 v35, v42
	v_mov_b32_e32 v42, v37
	v_pk_add_f32 v[34:35], v[34:35], v[42:43] neg_lo:[0,1] neg_hi:[0,1]
	v_cmp_gt_u32_e32 vcc, s21, v171
	v_mov_b32_e32 v36, v38
	s_nop 0
	v_cndmask_b32_e32 v42, v126, v35, vcc
	v_cmp_gt_u32_e32 vcc, s21, v172
	s_nop 1
	v_cndmask_b32_e32 v43, v126, v34, vcc
	v_pk_mul_f32 v[34:35], v[104:105], v[90:91]
	v_cmp_gt_u32_e32 vcc, s21, v173
	v_mov_b32_e32 v37, v34
	v_mov_b32_e32 v34, v39
	v_pk_add_f32 v[34:35], v[36:37], v[34:35] neg_lo:[0,1] neg_hi:[0,1]
	s_nop 0
	v_cndmask_b32_e32 v91, v126, v35, vcc
	v_cmp_gt_u32_e32 vcc, s21, v174
	s_nop 1
	v_cndmask_b32_e32 v104, v126, v34, vcc
	v_pk_mul_f32 v[34:35], v[102:103], v[164:165]
	v_cmp_gt_u32_e32 vcc, s21, v182
	v_pk_fma_f32 v[34:35], v[40:41], s[16:17], v[34:35] op_sel_hi:[1,0,1] neg_lo:[0,0,1] neg_hi:[0,0,1]
	s_nop 0
	v_cndmask_b32_e32 v105, v126, v35, vcc
	v_cmp_gt_u32_e32 vcc, s21, v183
	s_nop 1
	v_cndmask_b32_e32 v106, v126, v34, vcc
	v_max3_f32 v34, v114, v96, v106
	v_max3_f32 v34, v34, v49, v105
	v_max3_f32 v34, v34, v45, v108
	v_max3_f32 v34, v34, v44, v110
	v_max3_f32 v34, v34, v43, v104
	v_max3_f32 v34, v34, v42, v91
	ds_bpermute_b32 v35, v184, v34
	s_waitcnt lgkmcnt(0)
	v_max3_f32 v107, v133, v34, v35
	v_sub_f32_e32 v34, v46, v107
	v_sub_f32_e32 v111, v133, v107
	v_mov_b32_e32 v133, v107
	v_exp_f32_e32 v109, v34
	ds_read_b64_tr_b16 v[38:39], v124
	ds_read_b64_tr_b16 v[40:41], v124 offset:1024
	ds_read_b64_tr_b16 v[36:37], v124 offset:1088
	ds_read_b64_tr_b16 v[34:35], v124 offset:64
	v_sub_f32_e32 v112, v48, v107
	s_nop 1
	v_sub_f32_e32 v113, v0, v107
	v_exp_f32_e32 v112, v112
	s_nop 0
	v_exp_f32_e32 v113, v113
	v_cmp_lt_f32_e32 vcc, s23, v0
	v_sub_f32_e32 v0, v47, v107
	v_cmp_lt_f32_e64 s[2:3], s23, v46
	v_cndmask_b32_e32 v113, 0, v113, vcc
	s_nop 0
	v_cndmask_b32_e64 v46, 0, v109, s[2:3]
	s_nop 0
	v_exp_f32_e32 v0, v0
	v_cmp_lt_f32_e32 vcc, s23, v47
	s_nop 0
	s_nop 0
	v_cndmask_b32_e32 v47, 0, v0, vcc
	v_cmp_lt_f32_e32 vcc, s23, v48
	v_sub_f32_e32 v0, v96, v107
	s_nop 0
	v_cndmask_b32_e32 v48, 0, v112, vcc
	s_nop 1
	v_sub_f32_e32 v109, v49, v107
	v_exp_f32_e32 v0, v0
	s_nop 0
	v_exp_f32_e32 v109, v109
	v_cmp_lt_f32_e32 vcc, s23, v49
	s_nop 1
	v_cndmask_b32_e32 v49, 0, v109, vcc
	v_cmp_lt_f32_e32 vcc, s23, v96
	s_nop 1
	v_cndmask_b32_e32 v96, 0, v0, vcc
	v_sub_f32_e32 v0, v106, v107
	s_nop 1
	v_sub_f32_e32 v109, v105, v107
	v_exp_f32_e32 v0, v0
	s_nop 0
	v_exp_f32_e32 v109, v109
	v_cmp_lt_f32_e32 vcc, s23, v105
	s_nop 1
	v_cndmask_b32_e32 v105, 0, v109, vcc
	v_cmp_lt_f32_e32 vcc, s23, v106
	s_nop 1
	v_cndmask_b32_e32 v106, 0, v0, vcc
	v_sub_f32_e32 v0, v45, v107
	s_nop 1
	v_sub_f32_e32 v109, v44, v107
	v_exp_f32_e32 v0, v0
	s_nop 0
	v_exp_f32_e32 v109, v109
	v_cmp_lt_f32_e32 vcc, s23, v44
	s_nop 1
	v_cndmask_b32_e32 v109, 0, v109, vcc
	v_cmp_lt_f32_e32 vcc, s23, v45
	s_nop 1
	v_cndmask_b32_e32 v112, 0, v0, vcc
	v_sub_f32_e32 v0, v108, v107
	s_nop 1
	v_sub_f32_e32 v44, v110, v107
	v_exp_f32_e32 v0, v0
	s_nop 0
	v_exp_f32_e32 v44, v44
	v_cmp_lt_f32_e32 vcc, s23, v110
	s_nop 1
	v_cndmask_b32_e32 v110, 0, v44, vcc
	v_cmp_lt_f32_e32 vcc, s23, v108
	s_nop 1
	v_cndmask_b32_e32 v108, 0, v0, vcc
	v_sub_f32_e32 v0, v43, v107
	s_nop 1
	v_sub_f32_e32 v44, v42, v107
	v_exp_f32_e32 v0, v0
	s_nop 0
	v_exp_f32_e32 v44, v44
	v_cmp_lt_f32_e32 vcc, s23, v42
	v_bfe_u32 v45, v48, 16, 1
	s_nop 0
	v_cndmask_b32_e32 v114, 0, v44, vcc
	v_cmp_lt_f32_e32 vcc, s23, v43
	v_bfe_u32 v44, v47, 16, 1
	s_nop 0
	v_cndmask_b32_e32 v115, 0, v0, vcc
	v_sub_f32_e32 v0, v104, v107
	s_nop 1
	v_sub_f32_e32 v42, v91, v107
	v_exp_f32_e32 v0, v0
	s_nop 0
	v_exp_f32_e32 v42, v42
	v_cmp_lt_f32_e32 vcc, s23, v91
	v_bfe_u32 v43, v106, 16, 1
	v_add3_u32 v43, v106, v43, s28
	v_cndmask_b32_e32 v91, 0, v42, vcc
	v_cmp_lt_f32_e32 vcc, s23, v104
	s_nop 1
	v_cndmask_b32_e32 v104, 0, v0, vcc
	v_add_f32_e32 v0, v46, v48
	v_add_f32_e32 v0, v113, v0
	v_add_f32_e32 v0, v47, v0
	v_add_f32_e32 v0, v96, v0
	v_add_f32_e32 v0, v106, v0
	v_add_f32_e32 v0, v49, v0
	v_add_f32_e32 v0, v105, v0
	v_add_f32_e32 v0, v112, v0
	v_add_f32_e32 v0, v108, v0
	v_add_f32_e32 v0, v109, v0
	v_mov_b32_e32 v42, v111
	v_add_f32_e32 v0, v110, v0
	v_exp_f32_e32 v42, v42
	v_add_f32_e32 v0, v115, v0
	v_add_f32_e32 v0, v104, v0
	v_add_f32_e32 v111, v114, v0
	v_mov_b32_e32 v0, v42
	v_bfe_u32 v42, v105, 16, 1
	v_add3_u32 v48, v48, v45, s28
	v_add3_u32 v47, v47, v44, s28
	v_add3_u32 v42, v105, v42, s28
	v_bfe_u32 v44, v46, 16, 1
	v_bfe_u32 v45, v113, 16, 1
	v_bfe_u32 v105, v96, 16, 1
	v_bfe_u32 v106, v49, 16, 1
	v_add3_u32 v49, v49, v106, s28
	v_add3_u32 v96, v96, v105, s28
	v_add3_u32 v45, v113, v45, s28
	v_add3_u32 v44, v46, v44, s28
	v_lshrrev_b32_e32 v46, 16, v44
	v_lshrrev_b32_e32 v105, 16, v45
	v_lshrrev_b32_e32 v44, 16, v96
	v_lshrrev_b32_e32 v45, 16, v49
	v_pk_mul_f32 v[32:33], v[32:33], v[0:1] op_sel_hi:[1,0]
	v_pk_mul_f32 v[30:31], v[30:31], v[0:1] op_sel_hi:[1,0]
	v_pk_mul_f32 v[28:29], v[28:29], v[0:1] op_sel_hi:[1,0]
	v_pk_mul_f32 v[26:27], v[26:27], v[0:1] op_sel_hi:[1,0]
	v_pk_mul_f32 v[24:25], v[24:25], v[0:1] op_sel_hi:[1,0]
	v_pk_mul_f32 v[22:23], v[22:23], v[0:1] op_sel_hi:[1,0]
	v_pk_mul_f32 v[20:21], v[20:21], v[0:1] op_sel_hi:[1,0]
	v_pk_mul_f32 v[18:19], v[18:19], v[0:1] op_sel_hi:[1,0]
	v_pk_mul_f32 v[16:17], v[16:17], v[0:1] op_sel_hi:[1,0]
	v_and_or_b32 v45, v42, s29, v45
	v_and_or_b32 v44, v43, s29, v44
	v_and_or_b32 v43, v47, s29, v105
	v_and_or_b32 v42, v48, s29, v46
	v_pk_mul_f32 v[14:15], v[14:15], v[0:1] op_sel_hi:[1,0]
	v_pk_mul_f32 v[12:13], v[12:13], v[0:1] op_sel_hi:[1,0]
	v_pk_mul_f32 v[10:11], v[10:11], v[0:1] op_sel_hi:[1,0]
	v_pk_mul_f32 v[8:9], v[8:9], v[0:1] op_sel_hi:[1,0]
	v_pk_mul_f32 v[6:7], v[6:7], v[0:1] op_sel_hi:[1,0]
	v_pk_mul_f32 v[4:5], v[4:5], v[0:1] op_sel_hi:[1,0]
	v_pk_mul_f32 v[2:3], v[2:3], v[0:1] op_sel_hi:[1,0]
	s_waitcnt lgkmcnt(2)
	v_mfma_f32_32x32x16_bf16 v[18:33], v[38:41], v[42:45], v[18:33]
	s_waitcnt lgkmcnt(0)
	v_mfma_f32_32x32x16_bf16 v[2:17], v[34:37], v[42:45], v[2:17]
	v_bfe_u32 v34, v91, 16, 1
	v_bfe_u32 v35, v104, 16, 1
	v_bfe_u32 v36, v110, 16, 1
	v_bfe_u32 v37, v108, 16, 1
	v_add3_u32 v38, v108, v37, s28
	v_add3_u32 v39, v110, v36, s28
	v_add3_u32 v40, v104, v35, s28
	v_add3_u32 v41, v91, v34, s28
	v_bfe_u32 v34, v112, 16, 1
	v_bfe_u32 v35, v109, 16, 1
	v_bfe_u32 v36, v115, 16, 1
	v_bfe_u32 v37, v114, 16, 1
	v_add3_u32 v42, v114, v37, s28
	v_add3_u32 v43, v115, v36, s28
	v_add3_u32 v35, v109, v35, s28
	v_add3_u32 v34, v112, v34, s28
	v_lshrrev_b32_e32 v44, 16, v34
	v_lshrrev_b32_e32 v45, 16, v35
	ds_read_b64_tr_b16 v[34:35], v124 offset:2048
	ds_read_b64_tr_b16 v[36:37], v124 offset:3072
	v_lshrrev_b32_e32 v43, 16, v43
	v_lshrrev_b32_e32 v42, 16, v42
	v_and_or_b32 v41, v41, s29, v42
	v_and_or_b32 v40, v40, s29, v43
	v_and_or_b32 v39, v39, s29, v45
	v_and_or_b32 v38, v38, s29, v44
	ds_read_b64_tr_b16 v[44:45], v124 offset:3136
	ds_read_b64_tr_b16 v[42:43], v124 offset:2112
	s_waitcnt lgkmcnt(2)
	v_mfma_f32_32x32x16_bf16 v[18:33], v[34:37], v[38:41], v[18:33]
	v_add_f32_e32 v34, v91, v111
	ds_bpermute_b32 v35, v184, v34
	s_waitcnt lgkmcnt(0)
	s_waitcnt lgkmcnt(0)
	v_add_f32_e32 v34, v34, v35
	v_mfma_f32_32x32x16_bf16 v[2:17], v[42:45], v[38:41], v[2:17]
	v_fmac_f32_e32 v34, v130, v0
	v_mov_b32_e32 v130, v34
	s_branch .LBB0_626
